# tile-order arithmetic in the phase-1 and phase-10 tile headers simplified (row-group size is always 4: shift/mask instead of the generic division); on v079
# speedup vs baseline: 1.0004x; 1.0004x over previous
.LBB0_175:
	s_add_i32 s62, s62, 1
	s_mul_i32 s8, s62, s63
	s_mul_hi_u32 s9, s62, s67
	s_add_i32 s9, s9, s8
	s_mul_i32 s8, s62, s67
	s_add_u32 s46, s8, s16
	s_addc_u32 s47, s9, s64
	v_cmp_gt_i64_e64 s[8:9], s[46:47], v[146:147]
	s_and_b64 vcc, exec, s[8:9]
	s_cbranch_vccnz .LBB0_177
	s_ashr_i32 s11, s46, 31
	s_lshr_b32 s11, s11, 29
	s_add_i32 s11, s46, s11
	s_ashr_i32 s13, s11, 3
	s_and_b32 s11, s11, -8
	s_sub_i32 s11, s46, s11
	s_cmp_lt_i32 s11, 0
	s_cselect_b32 s17, s88, 0x140
	s_mul_i32 s11, s11, s17
	s_add_i32 s11, s11, s13
	s_mul_hi_i32 s13, s11, 0x66666667
	s_lshr_b32 s17, s13, 31
	s_ashr_i32 s13, s13, 5
	s_add_i32 s13, s13, s17
	s_lshl_b32 s17, s13, 2
	s_mulk_i32 s13, 0x50
	s_sub_i32 s11, s11, s13
	s_ashr_i32 s42, s11, 2
	s_and_b32 s11, s11, 3
	s_add_i32 s44, s17, s11

.LBB0_1090:
	s_add_i32 s51, s51, 1
	s_mul_i32 s0, s51, s52
	s_mul_hi_u32 s1, s51, s55
	s_add_i32 s1, s1, s0
	s_mul_i32 s0, s51, s55
	s_add_u32 s0, s0, s16
	s_addc_u32 s1, s1, s17
	v_cmp_gt_i64_e64 s[2:3], s[0:1], v[144:145]
	s_and_b64 vcc, exec, s[2:3]
	s_cbranch_vccnz .LBB0_1092
	s_ashr_i32 s12, s0, 31
	s_lshr_b32 s12, s12, 29
	s_add_i32 s12, s0, s12
	s_ashr_i32 s13, s12, 3
	s_and_b32 s12, s12, -8
	s_sub_i32 s12, s0, s12
	s_cmp_lt_i32 s12, 0
	s_cselect_b32 s28, s46, 0x160
	s_mul_i32 s12, s12, s28
	s_add_i32 s12, s12, s13
	s_mul_hi_i32 s13, s12, 0x2e8ba2e9
	s_lshr_b32 s28, s13, 31
	s_ashr_i32 s13, s13, 4
	s_add_i32 s13, s13, s28
	s_lshl_b32 s28, s13, 2
	s_mulk_i32 s13, 0x58
	s_sub_i32 s13, s12, s13
	s_ashr_i32 s12, s13, 2
	s_and_b32 s13, s13, 3
	s_add_i32 s36, s28, s13
